# L2 warm of pointwise weights: each WG touches 1/32 of the matrix one stage before all WGs read it
# speedup vs baseline: 1.0088x; 1.0088x over previous
; #define LAS __attribute__((address_space(3)))
; __device__ __forceinline__ float bf_lo(unsigned w) { return __uint_as_float(w << 16); }
; __device__ __forceinline__ float bf_hi(unsigned w) { return __uint_as_float(w & 0xffff0000u); }
; __device__ __forceinline__ void mixer_chunk(KP p, LAS unsigned char* lds, int l, int chunk) {
;     ...
; #pragma unroll
;             for (int r = 0; r < 38; ++r) {
;                 const unsigned yv = *(const LAS unsigned*)(Y + (t0 + r) * YLD + c); const float y0 = bf_lo(yv), y1 = bf_hi(yv);
; #pragma unroll
;                 for (int o = 0; o < 8; ++o) { const int j = r - o; if (j >= 0 && j <= 30) { a0[o] += w0[j] * y0; a1[o] += w1[j] * y1; } }
.LBB0_295:
	v_add_u32_e32 v67, s6, v0
	v_add_u32_e32 v68, 0x4200, v67
	ds_read2_b32 v[70:71], v68 offset1:132
	v_add_u32_e32 v72, 0x4600, v67
	ds_read2_b32 v[74:75], v72 offset0:8 offset1:140
	v_add_u32_e32 v76, 0x4a00, v67
	ds_read2_b32 v[78:79], v76 offset0:16 offset1:148
	s_waitcnt lgkmcnt(2)
	v_and_b32_e32 v69, 0xffff0000, v70
	v_lshlrev_b32_e32 v68, 16, v70
	v_add_u32_e32 v80, 0x4e00, v67
	s_waitcnt vmcnt(0)
	v_fma_f32 v68, v2, v68, v64
	v_fma_f32 v69, v3, v69, v65
	v_lshlrev_b32_e32 v70, 16, v71
	v_and_b32_e32 v71, 0xffff0000, v71
	ds_read2_b32 v[82:83], v80 offset0:24 offset1:156
	v_fmac_f32_e32 v68, v4, v70
	v_fmac_f32_e32 v69, v5, v71
	v_fma_f32 v70, v2, v70, v64
	v_fma_f32 v71, v3, v71, v65
	s_waitcnt lgkmcnt(2)
	v_lshlrev_b32_e32 v72, 16, v74
	v_and_b32_e32 v73, 0xffff0000, v74
	v_add_u32_e32 v84, 0x5200, v67
	v_fmac_f32_e32 v68, v6, v72
	v_fmac_f32_e32 v69, v7, v73
	v_fmac_f32_e32 v70, v4, v72
	v_fmac_f32_e32 v71, v5, v73
	v_fma_f32 v72, v2, v72, v64
	v_fma_f32 v73, v3, v73, v65
	v_lshlrev_b32_e32 v74, 16, v75
	v_and_b32_e32 v75, 0xffff0000, v75
	ds_read2_b32 v[84:85], v84 offset0:32 offset1:164
	v_fmac_f32_e32 v68, v8, v74
	v_fmac_f32_e32 v69, v9, v75
	v_fmac_f32_e32 v70, v6, v74
	v_fmac_f32_e32 v71, v7, v75
	v_fmac_f32_e32 v72, v4, v74
	v_fmac_f32_e32 v73, v5, v75
	v_fma_f32 v74, v2, v74, v64
	v_fma_f32 v75, v3, v75, v65
	s_waitcnt lgkmcnt(2)
	v_lshlrev_b32_e32 v76, 16, v78
	v_and_b32_e32 v77, 0xffff0000, v78
	v_fmac_f32_e32 v68, v10, v76
	v_fmac_f32_e32 v69, v11, v77
	v_fmac_f32_e32 v70, v8, v76
	v_fmac_f32_e32 v71, v9, v77
	v_fmac_f32_e32 v72, v6, v76
	v_fmac_f32_e32 v73, v7, v77
	v_fmac_f32_e32 v74, v4, v76
	v_fmac_f32_e32 v75, v5, v77
	v_fma_f32 v76, v2, v76, v64
	v_fma_f32 v77, v3, v77, v65
	v_lshlrev_b32_e32 v78, 16, v79
	v_and_b32_e32 v79, 0xffff0000, v79
	v_fmac_f32_e32 v68, v18, v78
	v_fmac_f32_e32 v69, v19, v79
	v_fmac_f32_e32 v70, v10, v78
	v_fmac_f32_e32 v71, v11, v79
	v_fmac_f32_e32 v72, v8, v78
	v_fmac_f32_e32 v73, v9, v79
	v_fmac_f32_e32 v74, v6, v78
	v_fmac_f32_e32 v75, v7, v79
	v_fmac_f32_e32 v76, v4, v78
	v_fmac_f32_e32 v77, v5, v79
	v_fma_f32 v78, v2, v78, v64
	v_fma_f32 v79, v3, v79, v65
	s_waitcnt lgkmcnt(1)
	v_lshlrev_b32_e32 v80, 16, v82
	v_and_b32_e32 v81, 0xffff0000, v82
	v_fmac_f32_e32 v68, v20, v80
	v_fmac_f32_e32 v69, v21, v81
	v_fmac_f32_e32 v70, v18, v80
	v_fmac_f32_e32 v71, v19, v81
	v_fmac_f32_e32 v72, v10, v80
	v_fmac_f32_e32 v73, v11, v81
	v_fmac_f32_e32 v74, v8, v80
	v_fmac_f32_e32 v75, v9, v81
	v_fmac_f32_e32 v76, v6, v80
	v_fmac_f32_e32 v77, v7, v81
	v_fmac_f32_e32 v78, v4, v80
	v_fmac_f32_e32 v79, v5, v81
	v_fma_f32 v80, v2, v80, v64
	v_fma_f32 v81, v3, v81, v65
	v_lshlrev_b32_e32 v82, 16, v83
	v_and_b32_e32 v83, 0xffff0000, v83
	v_fmac_f32_e32 v68, v22, v82
	v_fmac_f32_e32 v69, v23, v83
	v_fmac_f32_e32 v70, v20, v82
	v_fmac_f32_e32 v71, v21, v83
	v_fmac_f32_e32 v72, v18, v82
	v_fmac_f32_e32 v73, v19, v83
	v_fmac_f32_e32 v74, v10, v82
	v_fmac_f32_e32 v75, v11, v83
	v_fmac_f32_e32 v76, v8, v82
	v_fmac_f32_e32 v77, v9, v83
	v_fmac_f32_e32 v78, v6, v82
	v_fmac_f32_e32 v79, v7, v83
	v_fmac_f32_e32 v80, v4, v82
	v_fmac_f32_e32 v81, v5, v83
	v_fma_f32 v82, v2, v82, v64
	v_fma_f32 v83, v3, v83, v65
	s_waitcnt lgkmcnt(0)
	v_lshlrev_b32_e32 v86, 16, v84
	v_and_b32_e32 v84, 0xffff0000, v84
	v_fmac_f32_e32 v68, v12, v86
	v_fmac_f32_e32 v69, v13, v84
	v_fmac_f32_e32 v70, v22, v86
	v_fmac_f32_e32 v71, v23, v84
	v_fmac_f32_e32 v72, v20, v86
	v_fmac_f32_e32 v73, v21, v84
	v_fmac_f32_e32 v74, v18, v86
	v_fmac_f32_e32 v75, v19, v84
	v_fmac_f32_e32 v76, v10, v86
	v_fmac_f32_e32 v77, v11, v84
	v_fmac_f32_e32 v78, v8, v86
	v_fmac_f32_e32 v79, v9, v84
	v_fmac_f32_e32 v80, v6, v86
	v_fmac_f32_e32 v81, v7, v84
	v_fmac_f32_e32 v82, v4, v86
	v_fmac_f32_e32 v83, v5, v84
	v_lshlrev_b32_e32 v84, 16, v85
	v_and_b32_e32 v85, 0xffff0000, v85
	v_fmac_f32_e32 v68, v14, v84
	v_fmac_f32_e32 v70, v12, v84
	v_fmac_f32_e32 v72, v22, v84
	v_fmac_f32_e32 v74, v20, v84
	v_fmac_f32_e32 v76, v18, v84
	v_fmac_f32_e32 v78, v10, v84
	v_fmac_f32_e32 v80, v8, v84
	v_fmac_f32_e32 v82, v6, v84
	v_add_u32_e32 v84, 0x5600, v67
	v_fmac_f32_e32 v69, v15, v85
	v_fmac_f32_e32 v71, v13, v85
	v_fmac_f32_e32 v73, v23, v85
	v_fmac_f32_e32 v75, v21, v85
	v_fmac_f32_e32 v77, v19, v85
	v_fmac_f32_e32 v79, v11, v85
	v_fmac_f32_e32 v81, v9, v85
	v_fmac_f32_e32 v83, v7, v85
	ds_read2_b32 v[84:85], v84 offset0:40 offset1:172
	s_addk_i32 s6, 0x1080
	s_cmp_eq_u32 s6, 0
	s_waitcnt lgkmcnt(0)
	v_lshlrev_b32_e32 v86, 16, v84
	v_and_b32_e32 v84, 0xffff0000, v84
	v_fmac_f32_e32 v68, v16, v86
	v_fmac_f32_e32 v69, v17, v84
	v_fmac_f32_e32 v70, v14, v86
	v_fmac_f32_e32 v71, v15, v84
	v_fmac_f32_e32 v72, v12, v86
	v_fmac_f32_e32 v73, v13, v84
	v_fmac_f32_e32 v74, v22, v86
	v_fmac_f32_e32 v75, v23, v84
	v_fmac_f32_e32 v76, v20, v86
	v_fmac_f32_e32 v77, v21, v84
	v_fmac_f32_e32 v78, v18, v86
	v_fmac_f32_e32 v79, v19, v84
	v_fmac_f32_e32 v80, v10, v86
	v_fmac_f32_e32 v81, v11, v84
	v_fmac_f32_e32 v82, v8, v86
	v_fmac_f32_e32 v83, v9, v84
	v_lshlrev_b32_e32 v84, 16, v85
	v_and_b32_e32 v85, 0xffff0000, v85
	v_fmac_f32_e32 v68, v26, v84
	v_fmac_f32_e32 v70, v16, v84
	v_fmac_f32_e32 v72, v14, v84
	v_fmac_f32_e32 v74, v12, v84
	v_fmac_f32_e32 v76, v22, v84
	v_fmac_f32_e32 v78, v20, v84
	v_fmac_f32_e32 v80, v18, v84
	v_fmac_f32_e32 v82, v10, v84
	v_add_u32_e32 v84, 0x5a00, v67
	v_fmac_f32_e32 v69, v27, v85
	v_fmac_f32_e32 v71, v17, v85
	v_fmac_f32_e32 v73, v15, v85
	v_fmac_f32_e32 v75, v13, v85
	v_fmac_f32_e32 v77, v23, v85
	v_fmac_f32_e32 v79, v21, v85
	v_fmac_f32_e32 v81, v19, v85
	v_fmac_f32_e32 v83, v11, v85
	ds_read2_b32 v[84:85], v84 offset0:48 offset1:180
	s_waitcnt lgkmcnt(0)
; #define LAS __attribute__((address_space(3)))
; __device__ __forceinline__ float bf_lo(unsigned w) { return __uint_as_float(w << 16); }
; __device__ __forceinline__ float bf_hi(unsigned w) { return __uint_as_float(w & 0xffff0000u); }
; __device__ __forceinline__ void mixer_chunk(KP p, LAS unsigned char* lds, int l, int chunk) {
;     ...
;             for (int r = 0; r < 38; ++r) {
;                 const unsigned yv = *(const LAS unsigned*)(Y + (t0 + r) * YLD + c); const float y0 = bf_lo(yv), y1 = bf_hi(yv);
; #pragma unroll
;                 for (int o = 0; o < 8; ++o) { const int j = r - o; if (j >= 0 && j <= 30) { a0[o] += w0[j] * y0; a1[o] += w1[j] * y1; } }
	v_lshlrev_b32_e32 v86, 16, v84
	v_and_b32_e32 v84, 0xffff0000, v84
	v_fmac_f32_e32 v68, v28, v86
	v_fmac_f32_e32 v69, v29, v84
	v_fmac_f32_e32 v70, v26, v86
	v_fmac_f32_e32 v71, v27, v84
	v_fmac_f32_e32 v72, v16, v86
	v_fmac_f32_e32 v73, v17, v84
	v_fmac_f32_e32 v74, v14, v86
	v_fmac_f32_e32 v75, v15, v84
	v_fmac_f32_e32 v76, v12, v86
	v_fmac_f32_e32 v77, v13, v84
	v_fmac_f32_e32 v78, v22, v86
	v_fmac_f32_e32 v79, v23, v84
	v_fmac_f32_e32 v80, v20, v86
	v_fmac_f32_e32 v81, v21, v84
	v_fmac_f32_e32 v82, v18, v86
	v_fmac_f32_e32 v83, v19, v84
	v_lshlrev_b32_e32 v84, 16, v85
	v_and_b32_e32 v85, 0xffff0000, v85
	v_fmac_f32_e32 v68, v24, v84
	v_fmac_f32_e32 v70, v28, v84
	v_fmac_f32_e32 v72, v26, v84
	v_fmac_f32_e32 v74, v16, v84
	v_fmac_f32_e32 v76, v14, v84
	v_fmac_f32_e32 v78, v12, v84
	v_fmac_f32_e32 v80, v22, v84
	v_fmac_f32_e32 v82, v20, v84
	v_add_u32_e32 v84, 0x5e00, v67
	v_fmac_f32_e32 v69, v25, v85
	v_fmac_f32_e32 v71, v29, v85
	v_fmac_f32_e32 v73, v27, v85
	v_fmac_f32_e32 v75, v17, v85
	v_fmac_f32_e32 v77, v15, v85
	v_fmac_f32_e32 v79, v13, v85
	v_fmac_f32_e32 v81, v23, v85
	v_fmac_f32_e32 v83, v21, v85
	ds_read2_b32 v[84:85], v84 offset0:56 offset1:188
	s_waitcnt lgkmcnt(0)
	v_lshlrev_b32_e32 v86, 16, v84
	v_and_b32_e32 v84, 0xffff0000, v84
	v_fmac_f32_e32 v68, v34, v86
	v_fmac_f32_e32 v69, v35, v84
	v_fmac_f32_e32 v70, v24, v86
	v_fmac_f32_e32 v71, v25, v84
	v_fmac_f32_e32 v72, v28, v86
	v_fmac_f32_e32 v73, v29, v84
	v_fmac_f32_e32 v74, v26, v86
	v_fmac_f32_e32 v75, v27, v84
	v_fmac_f32_e32 v76, v16, v86
	v_fmac_f32_e32 v77, v17, v84
	v_fmac_f32_e32 v78, v14, v86
	v_fmac_f32_e32 v79, v15, v84
	v_fmac_f32_e32 v80, v12, v86
	v_fmac_f32_e32 v81, v13, v84
	v_fmac_f32_e32 v82, v22, v86
	v_fmac_f32_e32 v83, v23, v84
	v_lshlrev_b32_e32 v84, 16, v85
	v_and_b32_e32 v85, 0xffff0000, v85
	v_fmac_f32_e32 v68, v36, v84
	v_fmac_f32_e32 v70, v34, v84
	v_fmac_f32_e32 v72, v24, v84
	v_fmac_f32_e32 v74, v28, v84
	v_fmac_f32_e32 v76, v26, v84
	v_fmac_f32_e32 v78, v16, v84
	v_fmac_f32_e32 v80, v14, v84
	v_fmac_f32_e32 v82, v12, v84
	v_add_u32_e32 v84, 0x6200, v67
	v_fmac_f32_e32 v69, v37, v85
	v_fmac_f32_e32 v71, v35, v85
	v_fmac_f32_e32 v73, v25, v85
	v_fmac_f32_e32 v75, v29, v85
	v_fmac_f32_e32 v77, v27, v85
	v_fmac_f32_e32 v79, v17, v85
	v_fmac_f32_e32 v81, v15, v85
	v_fmac_f32_e32 v83, v13, v85
	ds_read2_b32 v[84:85], v84 offset0:64 offset1:196
	s_waitcnt lgkmcnt(0)
	v_lshlrev_b32_e32 v86, 16, v84
	v_and_b32_e32 v84, 0xffff0000, v84
	v_fmac_f32_e32 v68, v30, v86
	v_fmac_f32_e32 v69, v31, v84
	v_fmac_f32_e32 v70, v36, v86
	v_fmac_f32_e32 v71, v37, v84
	v_fmac_f32_e32 v72, v34, v86
	v_fmac_f32_e32 v73, v35, v84
	v_fmac_f32_e32 v74, v24, v86
	v_fmac_f32_e32 v75, v25, v84
	v_fmac_f32_e32 v76, v28, v86
	v_fmac_f32_e32 v77, v29, v84
	v_fmac_f32_e32 v78, v26, v86
	v_fmac_f32_e32 v79, v27, v84
	v_fmac_f32_e32 v80, v16, v86
	v_fmac_f32_e32 v81, v17, v84
	v_fmac_f32_e32 v82, v14, v86
	v_fmac_f32_e32 v83, v15, v84
	v_lshlrev_b32_e32 v84, 16, v85
	v_and_b32_e32 v85, 0xffff0000, v85
	v_fmac_f32_e32 v68, v32, v84
	v_fmac_f32_e32 v70, v30, v84
	v_fmac_f32_e32 v72, v36, v84
	v_fmac_f32_e32 v74, v34, v84
	v_fmac_f32_e32 v76, v24, v84
	v_fmac_f32_e32 v78, v28, v84
	v_fmac_f32_e32 v80, v26, v84
	v_fmac_f32_e32 v82, v16, v84
	v_add_u32_e32 v84, 0x6600, v67
	v_fmac_f32_e32 v69, v33, v85
	v_fmac_f32_e32 v71, v31, v85
	v_fmac_f32_e32 v73, v37, v85
	v_fmac_f32_e32 v75, v35, v85
	v_fmac_f32_e32 v77, v25, v85
	v_fmac_f32_e32 v79, v29, v85
	v_fmac_f32_e32 v81, v27, v85
	v_fmac_f32_e32 v83, v17, v85
	ds_read2_b32 v[84:85], v84 offset0:72 offset1:204
	s_waitcnt lgkmcnt(0)
	v_lshlrev_b32_e32 v86, 16, v84
	v_and_b32_e32 v84, 0xffff0000, v84
	v_fmac_f32_e32 v68, v42, v86
	v_fmac_f32_e32 v69, v43, v84
	v_fmac_f32_e32 v70, v32, v86
	v_fmac_f32_e32 v71, v33, v84
	v_fmac_f32_e32 v72, v30, v86
	v_fmac_f32_e32 v73, v31, v84
	v_fmac_f32_e32 v74, v36, v86
	v_fmac_f32_e32 v75, v37, v84
	v_fmac_f32_e32 v76, v34, v86
	v_fmac_f32_e32 v77, v35, v84
	v_fmac_f32_e32 v78, v24, v86
	v_fmac_f32_e32 v79, v25, v84
	v_fmac_f32_e32 v80, v28, v86
	v_fmac_f32_e32 v81, v29, v84
	v_fmac_f32_e32 v82, v26, v86
	v_fmac_f32_e32 v83, v27, v84
	v_lshlrev_b32_e32 v84, 16, v85
	v_and_b32_e32 v85, 0xffff0000, v85
	v_fmac_f32_e32 v68, v44, v84
	v_fmac_f32_e32 v70, v42, v84
	v_fmac_f32_e32 v72, v32, v84
	v_fmac_f32_e32 v74, v30, v84
	v_fmac_f32_e32 v76, v36, v84
	v_fmac_f32_e32 v78, v34, v84
	v_fmac_f32_e32 v80, v24, v84
	v_fmac_f32_e32 v82, v28, v84
	v_add_u32_e32 v84, 0x6a00, v67
	v_fmac_f32_e32 v69, v45, v85
	v_fmac_f32_e32 v71, v43, v85
	v_fmac_f32_e32 v73, v33, v85
	v_fmac_f32_e32 v75, v31, v85
	v_fmac_f32_e32 v77, v37, v85
	v_fmac_f32_e32 v79, v35, v85
	v_fmac_f32_e32 v81, v25, v85
	v_fmac_f32_e32 v83, v29, v85
	ds_read2_b32 v[84:85], v84 offset0:80 offset1:212
	s_waitcnt lgkmcnt(0)
	v_lshlrev_b32_e32 v86, 16, v84
	v_and_b32_e32 v84, 0xffff0000, v84
	v_fmac_f32_e32 v68, v46, v86
	v_fmac_f32_e32 v69, v47, v84
	v_fmac_f32_e32 v70, v44, v86
	v_fmac_f32_e32 v71, v45, v84
	v_fmac_f32_e32 v72, v42, v86
	v_fmac_f32_e32 v73, v43, v84
	v_fmac_f32_e32 v74, v32, v86
	v_fmac_f32_e32 v75, v33, v84
	v_fmac_f32_e32 v76, v30, v86
	v_fmac_f32_e32 v77, v31, v84
	v_fmac_f32_e32 v78, v36, v86
	v_fmac_f32_e32 v79, v37, v84
	v_fmac_f32_e32 v80, v34, v86
	v_fmac_f32_e32 v81, v35, v84
	v_fmac_f32_e32 v82, v24, v86
	v_fmac_f32_e32 v83, v25, v84
	v_lshlrev_b32_e32 v84, 16, v85
	v_and_b32_e32 v85, 0xffff0000, v85
	v_fmac_f32_e32 v68, v38, v84
	v_fmac_f32_e32 v70, v46, v84
	v_fmac_f32_e32 v72, v44, v84
	v_fmac_f32_e32 v74, v42, v84
	v_fmac_f32_e32 v76, v32, v84
	v_fmac_f32_e32 v78, v30, v84
	v_fmac_f32_e32 v80, v36, v84
	v_fmac_f32_e32 v82, v34, v84
	v_add_u32_e32 v84, 0x6e00, v67
	v_fmac_f32_e32 v69, v39, v85
	v_fmac_f32_e32 v71, v47, v85
	v_fmac_f32_e32 v73, v45, v85
	v_fmac_f32_e32 v75, v43, v85
	v_fmac_f32_e32 v77, v33, v85
	v_fmac_f32_e32 v79, v31, v85
	v_fmac_f32_e32 v81, v37, v85
	v_fmac_f32_e32 v83, v35, v85
	ds_read2_b32 v[84:85], v84 offset0:88 offset1:220
	s_waitcnt lgkmcnt(0)
; #define LAS __attribute__((address_space(3)))
; __device__ __forceinline__ unsigned pk2(float lo, float hi) { unsigned r; asm("v_cvt_pk_bf16_f32 %0, %1, %2" : "=v"(r) : "v"(lo), "v"(hi)); return r; }
; __device__ __forceinline__ float bf_lo(unsigned w) { return __uint_as_float(w << 16); }
; __device__ __forceinline__ float bf_hi(unsigned w) { return __uint_as_float(w & 0xffff0000u); }
; __device__ __forceinline__ void mixer_chunk(KP p, LAS unsigned char* lds, int l, int chunk) {
;     ...
;             for (int r = 0; r < 38; ++r) {
;                 const unsigned yv = *(const LAS unsigned*)(Y + (t0 + r) * YLD + c); const float y0 = bf_lo(yv), y1 = bf_hi(yv);
; #pragma unroll
;                 for (int o = 0; o < 8; ++o) { const int j = r - o; if (j >= 0 && j <= 30) { a0[o] += w0[j] * y0; a1[o] += w1[j] * y1; } }
;             }
; #pragma unroll
;             for (int o = 0; o < 8; ++o) *(LAS unsigned*)(CO + (t0 + o) * YLD + c) = pk2(a0[o], a1[o]);
	v_lshlrev_b32_e32 v86, 16, v84
	v_and_b32_e32 v84, 0xffff0000, v84
	v_fmac_f32_e32 v68, v40, v86
	v_fmac_f32_e32 v69, v41, v84
	v_fmac_f32_e32 v70, v38, v86
	v_fmac_f32_e32 v71, v39, v84
	v_fmac_f32_e32 v72, v46, v86
	v_fmac_f32_e32 v73, v47, v84
	v_fmac_f32_e32 v74, v44, v86
	v_fmac_f32_e32 v75, v45, v84
	v_fmac_f32_e32 v76, v42, v86
	v_fmac_f32_e32 v77, v43, v84
	v_fmac_f32_e32 v78, v32, v86
	v_fmac_f32_e32 v79, v33, v84
	v_fmac_f32_e32 v80, v30, v86
	v_fmac_f32_e32 v81, v31, v84
	v_fmac_f32_e32 v82, v36, v86
	v_fmac_f32_e32 v83, v37, v84
	v_lshlrev_b32_e32 v84, 16, v85
	v_and_b32_e32 v85, 0xffff0000, v85
	v_fmac_f32_e32 v68, v56, v84
	v_fmac_f32_e32 v70, v40, v84
	v_fmac_f32_e32 v72, v38, v84
	v_fmac_f32_e32 v74, v46, v84
	v_fmac_f32_e32 v76, v44, v84
	v_fmac_f32_e32 v78, v42, v84
	v_fmac_f32_e32 v80, v32, v84
	v_fmac_f32_e32 v82, v30, v84
	v_add_u32_e32 v84, 0x7200, v67
	v_fmac_f32_e32 v69, v57, v85
	v_fmac_f32_e32 v71, v41, v85
	v_fmac_f32_e32 v73, v39, v85
	v_fmac_f32_e32 v75, v47, v85
	v_fmac_f32_e32 v77, v45, v85
	v_fmac_f32_e32 v79, v43, v85
	v_fmac_f32_e32 v81, v33, v85
	v_fmac_f32_e32 v83, v31, v85
	ds_read2_b32 v[84:85], v84 offset0:96 offset1:228
	s_waitcnt lgkmcnt(0)
	v_lshlrev_b32_e32 v86, 16, v84
	v_and_b32_e32 v84, 0xffff0000, v84
	v_fmac_f32_e32 v68, v48, v86
	v_fmac_f32_e32 v69, v49, v84
	v_fmac_f32_e32 v70, v56, v86
	v_fmac_f32_e32 v71, v57, v84
	v_fmac_f32_e32 v72, v40, v86
	v_fmac_f32_e32 v73, v41, v84
	v_fmac_f32_e32 v74, v38, v86
	v_fmac_f32_e32 v75, v39, v84
	v_fmac_f32_e32 v76, v46, v86
	v_fmac_f32_e32 v77, v47, v84
	v_fmac_f32_e32 v78, v44, v86
	v_fmac_f32_e32 v79, v45, v84
	v_fmac_f32_e32 v80, v42, v86
	v_fmac_f32_e32 v81, v43, v84
	v_fmac_f32_e32 v82, v32, v86
	v_fmac_f32_e32 v83, v33, v84
	v_lshlrev_b32_e32 v84, 16, v85
	v_and_b32_e32 v85, 0xffff0000, v85
	v_fmac_f32_e32 v68, v50, v84
	v_fmac_f32_e32 v70, v48, v84
	v_fmac_f32_e32 v72, v56, v84
	v_fmac_f32_e32 v74, v40, v84
	v_fmac_f32_e32 v76, v38, v84
	v_fmac_f32_e32 v78, v46, v84
	v_fmac_f32_e32 v80, v44, v84
	v_fmac_f32_e32 v82, v42, v84
	v_add_u32_e32 v84, 0x7600, v67
	v_fmac_f32_e32 v69, v51, v85
	v_fmac_f32_e32 v71, v49, v85
	v_fmac_f32_e32 v73, v57, v85
	v_fmac_f32_e32 v75, v41, v85
	v_fmac_f32_e32 v77, v39, v85
	v_fmac_f32_e32 v79, v47, v85
	v_fmac_f32_e32 v81, v45, v85
	v_fmac_f32_e32 v83, v43, v85
	ds_read2_b32 v[84:85], v84 offset0:104 offset1:236
	s_waitcnt lgkmcnt(0)
	v_lshlrev_b32_e32 v86, 16, v84
	v_and_b32_e32 v84, 0xffff0000, v84
	v_fmac_f32_e32 v68, v52, v86
	v_fmac_f32_e32 v69, v53, v84
	v_fmac_f32_e32 v70, v50, v86
	v_fmac_f32_e32 v71, v51, v84
	v_fmac_f32_e32 v72, v48, v86
	v_fmac_f32_e32 v73, v49, v84
	v_fmac_f32_e32 v74, v56, v86
	v_fmac_f32_e32 v75, v57, v84
	v_fmac_f32_e32 v76, v40, v86
	v_fmac_f32_e32 v77, v41, v84
	v_fmac_f32_e32 v78, v38, v86
	v_fmac_f32_e32 v79, v39, v84
	v_fmac_f32_e32 v80, v46, v86
	v_fmac_f32_e32 v81, v47, v84
	v_fmac_f32_e32 v82, v44, v86
	v_fmac_f32_e32 v83, v45, v84
	v_lshlrev_b32_e32 v84, 16, v85
	v_and_b32_e32 v85, 0xffff0000, v85
	v_fmac_f32_e32 v68, v54, v84
	v_fmac_f32_e32 v70, v52, v84
	v_fmac_f32_e32 v72, v50, v84
	v_fmac_f32_e32 v74, v48, v84
	v_fmac_f32_e32 v76, v56, v84
	v_fmac_f32_e32 v78, v40, v84
	v_fmac_f32_e32 v80, v38, v84
	v_fmac_f32_e32 v82, v46, v84
	v_add_u32_e32 v84, 0x7a00, v67
	v_fmac_f32_e32 v69, v55, v85
	v_fmac_f32_e32 v71, v53, v85
	v_fmac_f32_e32 v73, v51, v85
	v_fmac_f32_e32 v75, v49, v85
	v_fmac_f32_e32 v77, v57, v85
	v_fmac_f32_e32 v79, v41, v85
	v_fmac_f32_e32 v81, v39, v85
	v_fmac_f32_e32 v83, v47, v85
	ds_read2_b32 v[84:85], v84 offset0:112 offset1:244
	s_waitcnt lgkmcnt(0)
	v_lshlrev_b32_e32 v86, 16, v84
	v_and_b32_e32 v84, 0xffff0000, v84
	v_fmac_f32_e32 v68, v58, v86
	v_fmac_f32_e32 v69, v59, v84
	v_fmac_f32_e32 v70, v54, v86
	v_fmac_f32_e32 v71, v55, v84
	v_fmac_f32_e32 v72, v52, v86
	v_fmac_f32_e32 v73, v53, v84
	v_fmac_f32_e32 v74, v50, v86
	v_fmac_f32_e32 v75, v51, v84
	v_fmac_f32_e32 v76, v48, v86
	v_fmac_f32_e32 v77, v49, v84
	v_fmac_f32_e32 v78, v56, v86
	v_fmac_f32_e32 v79, v57, v84
	v_fmac_f32_e32 v80, v40, v86
	v_fmac_f32_e32 v81, v41, v84
	v_fmac_f32_e32 v82, v38, v86
	v_fmac_f32_e32 v83, v39, v84
	v_lshlrev_b32_e32 v84, 16, v85
	v_and_b32_e32 v85, 0xffff0000, v85
	v_fmac_f32_e32 v68, v60, v84
	v_fmac_f32_e32 v70, v58, v84
	v_fmac_f32_e32 v72, v54, v84
	v_fmac_f32_e32 v74, v52, v84
	v_fmac_f32_e32 v76, v50, v84
	v_fmac_f32_e32 v78, v48, v84
	v_fmac_f32_e32 v80, v56, v84
	v_fmac_f32_e32 v82, v40, v84
	v_add_u32_e32 v84, 0x7e00, v67
	v_fmac_f32_e32 v69, v61, v85
	v_fmac_f32_e32 v71, v59, v85
	v_fmac_f32_e32 v73, v55, v85
	v_fmac_f32_e32 v75, v53, v85
	v_fmac_f32_e32 v77, v51, v85
	v_fmac_f32_e32 v79, v49, v85
	v_fmac_f32_e32 v81, v57, v85
	v_fmac_f32_e32 v83, v41, v85
	ds_read2_b32 v[84:85], v84 offset0:120 offset1:252
	s_waitcnt lgkmcnt(0)
	v_lshlrev_b32_e32 v86, 16, v84
	v_and_b32_e32 v84, 0xffff0000, v84
	v_fmac_f32_e32 v69, v63, v84
	v_fmac_f32_e32 v70, v60, v86
	v_fmac_f32_e32 v71, v61, v84
	v_fmac_f32_e32 v72, v58, v86
	v_fmac_f32_e32 v73, v59, v84
	v_fmac_f32_e32 v74, v54, v86
	v_fmac_f32_e32 v75, v55, v84
	v_fmac_f32_e32 v76, v52, v86
	v_fmac_f32_e32 v77, v53, v84
	v_fmac_f32_e32 v78, v50, v86
	v_fmac_f32_e32 v79, v51, v84
	v_fmac_f32_e32 v80, v48, v86
	v_fmac_f32_e32 v81, v49, v84
	v_fmac_f32_e32 v82, v56, v86
	v_fmac_f32_e32 v83, v57, v84
	v_lshlrev_b32_e32 v84, 16, v85
	v_and_b32_e32 v85, 0xffff0000, v85
	v_fmac_f32_e32 v70, v62, v84
	v_fmac_f32_e32 v72, v60, v84
	v_fmac_f32_e32 v74, v58, v84
	v_fmac_f32_e32 v76, v54, v84
	v_fmac_f32_e32 v78, v52, v84
	v_fmac_f32_e32 v80, v50, v84
	v_fmac_f32_e32 v82, v48, v84
	v_add_u32_e32 v84, 0x8400, v67
	v_fmac_f32_e32 v71, v63, v85
	v_fmac_f32_e32 v73, v61, v85
	v_fmac_f32_e32 v75, v59, v85
	v_fmac_f32_e32 v77, v55, v85
	v_fmac_f32_e32 v79, v53, v85
	v_fmac_f32_e32 v81, v51, v85
	v_fmac_f32_e32 v83, v49, v85
	ds_read2_b32 v[84:85], v84 offset1:132
	v_fmac_f32_e32 v68, v62, v86
	v_cvt_pk_bf16_f32 v68, v68, v69
	v_add_u32_e32 v69, 0x19a00, v67
	ds_write_b32 v69, v68
	s_waitcnt lgkmcnt(1)
; #define LAS __attribute__((address_space(3)))
; __device__ __forceinline__ unsigned pk2(float lo, float hi) { unsigned r; asm("v_cvt_pk_bf16_f32 %0, %1, %2" : "=v"(r) : "v"(lo), "v"(hi)); return r; }
; __device__ __forceinline__ float bf_lo(unsigned w) { return __uint_as_float(w << 16); }
; __device__ __forceinline__ float bf_hi(unsigned w) { return __uint_as_float(w & 0xffff0000u); }
; __device__ __forceinline__ void mixer_chunk(KP p, LAS unsigned char* lds, int l, int chunk) {
;     ...
;             for (int r = 0; r < 38; ++r) {
;                 const unsigned yv = *(const LAS unsigned*)(Y + (t0 + r) * YLD + c); const float y0 = bf_lo(yv), y1 = bf_hi(yv);
; #pragma unroll
;                 for (int o = 0; o < 8; ++o) { const int j = r - o; if (j >= 0 && j <= 30) { a0[o] += w0[j] * y0; a1[o] += w1[j] * y1; } }
;             }
; #pragma unroll
;             for (int o = 0; o < 8; ++o) *(LAS unsigned*)(CO + (t0 + o) * YLD + c) = pk2(a0[o], a1[o]);
;     ...
;     for (int i = 0; i < 6; ++i) { const int q = tid + 512 * i, r = q / 24, pc = q % 24; sq[i] = *(const u32x4*)(zb + (size_t)(c0 + r) * DIN_P + ZC_CQ + 8 * pc); }
	v_lshlrev_b32_e32 v86, 16, v84
	v_and_b32_e32 v84, 0xffff0000, v84
	v_fmac_f32_e32 v73, v63, v84
	v_fmac_f32_e32 v74, v60, v86
	v_fmac_f32_e32 v75, v61, v84
	v_fmac_f32_e32 v76, v58, v86
	v_fmac_f32_e32 v77, v59, v84
	v_fmac_f32_e32 v78, v54, v86
	v_fmac_f32_e32 v79, v55, v84
	v_fmac_f32_e32 v80, v52, v86
	v_fmac_f32_e32 v81, v53, v84
	v_fmac_f32_e32 v82, v50, v86
	v_fmac_f32_e32 v83, v51, v84
	v_lshlrev_b32_e32 v84, 16, v85
	v_and_b32_e32 v85, 0xffff0000, v85
	v_fmac_f32_e32 v74, v62, v84
	v_fmac_f32_e32 v76, v60, v84
	v_fmac_f32_e32 v78, v58, v84
	v_fmac_f32_e32 v80, v54, v84
	v_fmac_f32_e32 v82, v52, v84
	v_add_u32_e32 v84, 0x8800, v67
	v_fmac_f32_e32 v75, v63, v85
	v_fmac_f32_e32 v77, v61, v85
	v_fmac_f32_e32 v79, v59, v85
	v_fmac_f32_e32 v81, v55, v85
	v_fmac_f32_e32 v83, v53, v85
	ds_read2_b32 v[84:85], v84 offset0:8 offset1:140
	v_fmac_f32_e32 v72, v62, v86
	v_cvt_pk_bf16_f32 v68, v70, v71
	v_add_u32_e32 v69, 0x19c10, v67
	ds_write_b32 v69, v68
	s_waitcnt lgkmcnt(1)
	v_lshlrev_b32_e32 v86, 16, v84
	v_and_b32_e32 v84, 0xffff0000, v84
	v_fmac_f32_e32 v77, v63, v84
	v_fmac_f32_e32 v78, v60, v86
	v_fmac_f32_e32 v79, v61, v84
	v_fmac_f32_e32 v80, v58, v86
	v_fmac_f32_e32 v81, v59, v84
	v_fmac_f32_e32 v82, v54, v86
	v_fmac_f32_e32 v83, v55, v84
	v_lshlrev_b32_e32 v84, 16, v85
	v_and_b32_e32 v85, 0xffff0000, v85
	v_fmac_f32_e32 v78, v62, v84
	v_fmac_f32_e32 v80, v60, v84
	v_fmac_f32_e32 v82, v58, v84
	v_add_u32_e32 v84, 0x8c00, v67
	v_fmac_f32_e32 v79, v63, v85
	v_fmac_f32_e32 v81, v61, v85
	v_fmac_f32_e32 v83, v59, v85
	ds_read2_b32 v[84:85], v84 offset0:16 offset1:148
	v_cvt_pk_bf16_f32 v68, v72, v73
	v_add_u32_e32 v69, 0x19e20, v67
	ds_write_b32 v69, v68
	v_cvt_pk_bf16_f32 v68, v74, v75
	v_add_u32_e32 v69, 0x1a030, v67
	v_fmac_f32_e32 v76, v62, v86
	ds_write_b32 v69, v68
	v_cvt_pk_bf16_f32 v68, v76, v77
	v_add_u32_e32 v69, 0x1a240, v67
	s_waitcnt lgkmcnt(2)
	v_lshlrev_b32_e32 v86, 16, v84
	v_and_b32_e32 v84, 0xffff0000, v84
	ds_write_b32 v69, v68
	v_cvt_pk_bf16_f32 v68, v78, v79
	v_add_u32_e32 v69, 0x1a450, v67
	v_fmac_f32_e32 v80, v62, v86
	v_fmac_f32_e32 v81, v63, v84
	v_fmac_f32_e32 v82, v60, v86
	v_fmac_f32_e32 v83, v61, v84
	v_lshlrev_b32_e32 v84, 16, v85
	v_and_b32_e32 v85, 0xffff0000, v85
	ds_write_b32 v69, v68
	v_cvt_pk_bf16_f32 v68, v80, v81
	v_add_u32_e32 v69, 0x1a660, v67
	v_add_u32_e32 v67, 0x1a870, v67
	v_fmac_f32_e32 v83, v63, v85
	v_fmac_f32_e32 v82, v62, v84
	ds_write_b32 v69, v68
	v_cvt_pk_bf16_f32 v68, v82, v83
	ds_write_b32 v67, v68
	s_cbranch_scc0 .LBB0_295
	v_mul_hi_i32 v0, v204, s63
	v_lshrrev_b32_e32 v2, 31, v0
	v_ashrrev_i32_e32 v0, 2, v0
	v_add_u32_e32 v74, v0, v2
	v_mul_lo_u32 v0, v74, 24
	v_sub_u32_e32 v75, v204, v0
	v_add_u32_e32 v0, s25, v74
	v_mov_b64_e32 v[38:39], s[44:45]
	v_mad_i64_i32 v[2:3], s[6:7], v0, s65, v[38:39]
	v_mul_hi_i32 v0, v206, s63
	v_lshrrev_b32_e32 v6, 31, v0
	v_ashrrev_i32_e32 v0, 2, v0
	v_add_u32_e32 v76, v0, v6
	v_mul_lo_u32 v0, v76, 24
	v_sub_u32_e32 v77, v206, v0
	v_add_u32_e32 v0, s25, v76
	v_mad_i64_i32 v[6:7], s[6:7], v0, s65, v[38:39]
	v_mul_hi_i32 v0, v212, s63
	v_lshrrev_b32_e32 v10, 31, v0
	v_ashrrev_i32_e32 v0, 2, v0
	v_add_u32_e32 v78, v0, v10
	v_mul_lo_u32 v0, v78, 24
	v_sub_u32_e32 v79, v212, v0
	v_add_u32_e32 v0, s25, v78
	v_mad_i64_i32 v[10:11], s[6:7], v0, s65, v[38:39]
	v_mul_hi_i32 v0, v211, s63
	v_lshrrev_b32_e32 v14, 31, v0
	v_ashrrev_i32_e32 v0, 2, v0
	v_add_u32_e32 v80, v0, v14
	v_mul_lo_u32 v0, v80, 24
	v_sub_u32_e32 v81, v211, v0
	v_add_u32_e32 v0, s25, v80
	v_mad_i64_i32 v[14:15], s[6:7], v0, s65, v[38:39]
	v_mul_hi_i32 v0, v210, s63
	v_lshrrev_b32_e32 v18, 31, v0
	v_ashrrev_i32_e32 v0, 2, v0
	v_add_u32_e32 v82, v0, v18
	v_mul_lo_u32 v0, v82, 24
	v_sub_u32_e32 v83, v210, v0
	v_add_u32_e32 v0, s25, v82
	v_add_u32_e32 v218, 0xa00, v204
	v_mad_i64_i32 v[18:19], s[6:7], v0, s65, v[38:39]
	v_mul_hi_i32 v0, v218, s63
	v_lshrrev_b32_e32 v22, 31, v0
	v_ashrrev_i32_e32 v0, 2, v0
	s_waitcnt lgkmcnt(0)
	s_barrier
; __device__ __forceinline__ void mixer_chunk(KP p, LAS unsigned char* lds, int l, int chunk) {
;     ...
;     u32x4 sq[6], sk[4];
; #pragma unroll
;     for (int i = 0; i < 6; ++i) { const int q = tid + 512 * i, r = q / 24, pc = q % 24; sq[i] = *(const u32x4*)(zb + (size_t)(c0 + r) * DIN_P + ZC_CQ + 8 * pc); }
; #pragma unroll
;     for (int i = 0; i < 4; ++i) { const int q = tid + 512 * i, r = q >> 4, pc = q & 15; sk[i] = *(const u32x4*)(zb + (size_t)(c0 + r) * DIN_P + ZC_CKV + 8 * pc); }
;     {
;         const f32x4 lg = *(const f32x4*)(p->conv_ln_g + l * 256 + 4 * lane), lb = *(const f32x4*)(p->conv_ln_b + l * 256 + 4 * lane);
	v_add_u32_e32 v84, v0, v22
	s_load_dwordx4 s[40:43], s[0:1], 0x30
	v_mul_lo_u32 v0, v84, 24
	v_sub_u32_e32 v85, v218, v0
	v_add_u32_e32 v0, s25, v84
	v_ashrrev_i32_e32 v86, 4, v204
	v_ashrrev_i32_e32 v88, 4, v206
	v_ashrrev_i32_e32 v89, 4, v212
	v_ashrrev_i32_e32 v90, 4, v211
	v_mad_i64_i32 v[22:23], s[6:7], v0, s65, v[38:39]
	v_add_u32_e32 v0, s25, v86
	v_add_u32_e32 v30, s25, v88
	v_add_u32_e32 v34, s25, v89
	v_add_u32_e32 v40, s25, v90
	v_and_b32_e32 v87, 0x78, v209
	v_mad_i64_i32 v[26:27], s[6:7], v0, s65, v[38:39]
	v_mad_i64_i32 v[30:31], s[6:7], v30, s65, v[38:39]
	v_mad_i64_i32 v[34:35], s[6:7], v34, s65, v[38:39]
	v_mad_i64_i32 v[38:39], s[6:7], v40, s65, v[38:39]
	v_lshlrev_b32_e32 v0, 1, v87
	s_waitcnt lgkmcnt(0)
	s_add_u32 s6, s40, s36
	v_lshlrev_b32_e32 v4, 3, v75
	v_lshlrev_b32_e32 v8, 3, v77
	v_lshlrev_b32_e32 v12, 3, v79
	v_lshlrev_b32_e32 v16, 3, v81
	v_lshlrev_b32_e32 v20, 3, v83
	v_lshlrev_b32_e32 v24, 3, v85
	v_lshl_add_u64 v[26:27], v[26:27], 0, v[0:1]
	v_lshl_add_u64 v[30:31], v[30:31], 0, v[0:1]
	v_lshl_add_u64 v[34:35], v[34:35], 0, v[0:1]
	v_lshl_add_u64 v[38:39], v[38:39], 0, v[0:1]
	s_addc_u32 s7, s41, s37
	v_lshlrev_b32_e32 v0, 2, v66
	v_ashrrev_i32_e32 v5, 31, v4
	v_ashrrev_i32_e32 v9, 31, v8
	v_ashrrev_i32_e32 v13, 31, v12
	v_ashrrev_i32_e32 v17, 31, v16
	v_ashrrev_i32_e32 v21, 31, v20
	v_ashrrev_i32_e32 v25, 31, v24
	global_load_dwordx4 v[42:45], v0, s[6:7]
	s_add_u32 s6, s42, s36
	v_lshl_add_u64 v[2:3], v[4:5], 1, v[2:3]
	v_lshl_add_u64 v[6:7], v[8:9], 1, v[6:7]
	v_lshl_add_u64 v[10:11], v[12:13], 1, v[10:11]
	v_lshl_add_u64 v[14:15], v[16:17], 1, v[14:15]
	v_lshl_add_u64 v[18:19], v[20:21], 1, v[18:19]
	v_lshl_add_u64 v[22:23], v[24:25], 1, v[22:23]
	s_addc_u32 s7, s43, s37
	global_load_dwordx4 v[2:5], v[2:3], off offset:1024
	v_and_b32_e32 v50, 64, v193
	global_load_dwordx4 v[6:9], v[6:7], off offset:1024
	v_add_u32_e32 v50, 64, v50
	global_load_dwordx4 v[10:13], v[10:11], off offset:1024
	v_xor_b32_e32 v51, 1, v193
	global_load_dwordx4 v[14:17], v[14:15], off offset:1024
	v_cmp_lt_i32_e32 vcc, v51, v50
	global_load_dwordx4 v[18:21], v[18:19], off offset:1024
	s_lshl_b32 s88, s55, 4
	global_load_dwordx4 v[22:25], v[22:23], off offset:1024
	v_cndmask_b32_e32 v51, v193, v51, vcc
	global_load_dwordx4 v[26:29], v[26:27], off offset:1408
	v_lshlrev_b32_e32 v213, 2, v51
	global_load_dwordx4 v[30:33], v[30:31], off offset:1408
	v_xor_b32_e32 v51, 2, v193
	global_load_dwordx4 v[34:37], v[34:35], off offset:1408
	v_cmp_lt_i32_e32 vcc, v51, v50
	global_load_dwordx4 v[38:41], v[38:39], off offset:1408
	s_mov_b64 s[40:41], -1
	global_load_dwordx4 v[46:49], v0, s[6:7]
	s_cselect_b32 s98, 1, 0
	s_mul_i32 s100, s22, 0x20000
	s_add_u32 s100, s100, 0x5600000
	s_add_u32 s100, s94, s100
	s_addc_u32 s101, s95, 0
	s_lshr_b32 s99, s2, 3
	s_mul_i32 s99, s99, 0x1000
	v_and_b32_e32 v249, 31, v167
	v_lshlrev_b32_e32 v249, 7, v249
	v_add_u32_e32 v249, s99, v249
	s_cmp_lg_u32 s98, 0
	global_load_dword v250, v249, s[100:101]
	v_cndmask_b32_e32 v51, v193, v51, vcc
	v_lshlrev_b32_e32 v214, 2, v51
	v_xor_b32_e32 v51, 4, v193
	v_cmp_lt_i32_e32 vcc, v51, v50
	v_lshl_add_u32 v0, v66, 1, s69
	s_mov_b32 s6, 0
	v_cndmask_b32_e32 v51, v193, v51, vcc
	v_lshlrev_b32_e32 v91, 2, v51
	v_xor_b32_e32 v51, 8, v193
	v_cmp_lt_i32_e32 vcc, v51, v50
	s_nop 1
	v_cndmask_b32_e32 v51, v193, v51, vcc
	v_lshlrev_b32_e32 v92, 2, v51
	v_xor_b32_e32 v51, 16, v193
	v_cmp_lt_i32_e32 vcc, v51, v50
	s_nop 1
	v_cndmask_b32_e32 v51, v193, v51, vcc
	v_lshlrev_b32_e32 v207, 2, v51
	v_xor_b32_e32 v51, 32, v193
	v_cmp_lt_i32_e32 vcc, v51, v50
	s_nop 1
	v_cndmask_b32_e32 v50, v193, v51, vcc
	v_lshlrev_b32_e32 v208, 2, v50
